# wkv prep: next-item row prefetch de-serialized (10 loads in flight), per-head parameters kept resident in 88 spare VGPRs after first item; P6 gate loads batched
# speedup vs baseline: 1.0720x; 1.0291x over previous
.LBB0_769:
.LBB0_770:
	v_writelane_b32 v240, s90, 18
	s_andn2_b64 vcc, exec, s[0:1]
	v_writelane_b32 v240, s88, 19
	s_nop 1
	v_writelane_b32 v240, s89, 20
	s_cbranch_vccnz .LBB0_942
	v_readlane_b32 s0, v241, 33
	v_readlane_b32 s4, v241, 37
	v_readlane_b32 s5, v241, 38
	s_add_u32 s30, s4, 0x1000
	s_addc_u32 s31, s5, 0
	s_add_u32 s68, s4, 0x1800
	s_addc_u32 s69, s5, 0
	v_readlane_b32 s13, v241, 46
	s_add_u32 s70, s4, 0x1900
	v_readlane_b32 s1, v241, 34
	v_readlane_b32 s2, v241, 35
	v_readlane_b32 s3, v241, 36
	v_readlane_b32 s6, v241, 39
	v_readlane_b32 s7, v241, 40
	v_readlane_b32 s14, v241, 47
	v_readlane_b32 s15, v241, 48
	s_addc_u32 s71, s5, 0
	s_mov_b32 s13, 0
	s_add_i32 s0, 0, 0xfc00
	v_readlane_b32 s12, v241, 45
	v_mov_b32_e32 v122, s0
	v_readlane_b32 s0, v241, 8
	v_mbcnt_hi_u32_b32 v129, -1, v164
	s_mov_b32 s14, s13
	s_mov_b32 s15, s13
	v_readlane_b32 s10, v241, 43
	v_readlane_b32 s11, v241, 44
	s_add_i32 s97, 0, 0x12000
	v_readlane_b32 s2, v241, 10
	v_readlane_b32 s3, v241, 11
	v_readlane_b32 s4, v241, 12
	v_readlane_b32 s5, v241, 13
	v_readlane_b32 s6, v241, 14
	v_readlane_b32 s7, v241, 15
	s_add_i32 s0, 0, 0x14400
	v_and_b32_e32 v40, 64, v129
	s_mov_b32 s12, s13
	v_mov_b64_e32 v[154:155], s[14:15]
	s_movk_i32 s96, 0x90
	v_mov_b32_e32 v121, s97
	v_mov_b32_e32 v123, s7
	v_mov_b32_e32 v124, s5
	v_mov_b32_e32 v125, s6
	v_mov_b32_e32 v126, s4
	v_mov_b32_e32 v127, s0
	v_mov_b32_e32 v43, 0
	s_mov_b32 s91, 0xbfb8aa3b
	s_mov_b32 s3, 0x800000
	s_mov_b32 s10, 0x3f317217
	s_mov_b32 s11, 0x7f800000
	v_mov_b32_e32 v128, 0x41b17218
	v_xor_b32_e32 v130, 1, v129
	v_add_u32_e32 v131, 64, v40
	v_xor_b32_e32 v132, 2, v129
	v_xor_b32_e32 v133, 4, v129
	s_add_i32 s94, 0, 0x1f800
	v_mov_b32_e32 v134, 0x260
	s_add_i32 s95, 0, 0x1d400
	s_add_i32 s33, 0, 0x1b000
	s_add_i32 s92, 0, 0x18c00
	s_movk_i32 s93, 0x7fff
	v_mov_b64_e32 v[152:153], s[12:13]
	s_add_i32 s90, 0, 0x21c00
	s_mov_b64 s[14:15], 0x800
	v_readlane_b32 s2, v240, 18
	v_readlane_b32 s8, v241, 41
	v_readlane_b32 s9, v241, 42
	v_readlane_b32 s1, v241, 9
	v_writelane_b32 v241, s0, 8
	s_mov_b32 s101, 0
	s_branch .LBB0_773
.LBB0_772:
	s_or_b64 exec, exec, s[0:1]
	v_readlane_b32 s100, v240, 19
	s_nop 0
	s_and_b32 s100, s100, 7
	s_cmp_eq_u32 s100, 0
	s_cselect_b32 s101, 1, 0
	v_mov_b32_e32 v61, v43
	v_lshl_add_u64 v[40:41], v[46:47], 0, v[60:61]
	global_store_dwordx2 v[40:41], v[44:45], off nt
	s_waitcnt lgkmcnt(0)
	s_barrier
	s_and_b64 vcc, exec, s[4:5]
	s_cbranch_vccnz .LBB0_942
.LBB0_773:
	v_mov_b32_e32 v137, v174
	s_bfe_u32 s8, s2, 0x60003
	v_lshlrev_b32_e32 v136, 3, v137
	v_and_b32_e32 v142, 56, v136
	v_lshlrev_b32_e32 v144, 2, v142
	s_cmp_lg_u32 s101, 0
	s_cbranch_scc1 .Lres_skip_7
	global_load_dwordx4 v[156:159], v144, s[68:69]
	global_load_dwordx4 v[160:163], v144, s[68:69] offset:16
	global_load_dwordx4 v[168:171], v144, s[70:71]
	global_load_dwordx4 v[176:179], v144, s[70:71] offset:16
	s_waitcnt vmcnt(0)
.Lres_skip_7:
	s_waitcnt vmcnt(8)
	s_lshl_b32 s4, s8, 6
	v_ashrrev_i32_e32 v141, 3, v137
	v_add_u32_e32 v88, s4, v141
	v_lshlrev_b32_e32 v66, 16, v28
	v_cmp_lt_i32_e32 vcc, 0, v88
	v_lshlrev_b32_e32 v42, 16, v24
	v_and_b32_e32 v67, 0xffff0000, v28
	v_cndmask_b32_e32 v66, 0, v66, vcc
	v_and_b32_e32 v72, 0xffff0000, v24
	v_and_b32_e32 v80, 0xffff0000, v31
	v_and_b32_e32 v81, 0xffff0000, v36
	v_sub_f32_e32 v88, v66, v42
	v_cndmask_b32_e32 v89, 0, v67, vcc
	v_and_b32_e32 v79, 0xffff0000, v27
	v_cndmask_b32_e32 v80, 0, v80, vcc
	v_cndmask_b32_e32 v67, 0, v81, vcc
	v_sub_f32_e32 v81, v89, v72
	v_sub_f32_e32 v80, v80, v79
	v_lshlrev_b32_e32 v78, 16, v31
	v_lshlrev_b32_e32 v68, 16, v29
	v_lshlrev_b32_e32 v77, 16, v27
	v_cndmask_b32_e32 v78, 0, v78, vcc
	v_lshlrev_b32_e32 v73, 16, v25
	v_and_b32_e32 v69, 0xffff0000, v29
	v_lshlrev_b32_e32 v82, 16, v36
	v_cndmask_b32_e32 v90, 0, v68, vcc
	v_sub_f32_e32 v78, v78, v77
	v_and_b32_e32 v74, 0xffff0000, v25
	v_and_b32_e32 v83, 0xffff0000, v37
	v_and_b32_e32 v87, 0xffff0000, v39
	v_cndmask_b32_e32 v91, 0, v69, vcc
	v_cndmask_b32_e32 v66, 0, v82, vcc
	v_sub_f32_e32 v82, v90, v73
	v_and_b32_e32 v65, 0xffff0000, v35
	v_lshlrev_b32_e32 v64, 16, v35
	v_cndmask_b32_e32 v69, 0, v83, vcc
	v_sub_f32_e32 v83, v91, v74
	v_lshlrev_b32_e32 v70, 16, v30
	v_lshlrev_b32_e32 v75, 16, v26
	v_and_b32_e32 v71, 0xffff0000, v30
	v_lshlrev_b32_e32 v84, 16, v37
	v_cndmask_b32_e32 v92, 0, v70, vcc
	v_and_b32_e32 v76, 0xffff0000, v26
	v_and_b32_e32 v85, 0xffff0000, v38
	v_cndmask_b32_e32 v93, 0, v71, vcc
	v_cndmask_b32_e32 v68, 0, v84, vcc
	v_sub_f32_e32 v84, v92, v75
	v_cndmask_b32_e32 v71, 0, v85, vcc
	v_sub_f32_e32 v85, v93, v76
	v_and_b32_e32 v41, 0xffff0000, v32
	v_lshlrev_b32_e32 v40, 16, v32
	v_pk_add_f32 v[66:67], v[66:67], v[40:41] neg_lo:[0,1] neg_hi:[0,1]
	v_lshlrev_b32_e32 v86, 16, v38
	v_and_b32_e32 v61, 0xffff0000, v33
	v_lshlrev_b32_e32 v60, 16, v33
	v_and_b32_e32 v63, 0xffff0000, v34
	v_lshlrev_b32_e32 v62, 16, v34
	v_cndmask_b32_e32 v70, 0, v86, vcc
	v_pk_add_f32 v[68:69], v[68:69], v[60:61] neg_lo:[0,1] neg_hi:[0,1]
	v_pk_add_f32 v[70:71], v[70:71], v[62:63] neg_lo:[0,1] neg_hi:[0,1]
	s_movk_i32 s0, 0x100
	s_and_b32 s5, s2, 7
	v_cmp_gt_u32_e64 s[0:1], s0, v137
	s_lshl_b32 s9, s5, 6
	s_lshl_b32 s12, s5, 13
	v_and_b32_e32 v135, 15, v137
	v_or_b32_e32 v146, s9, v142
	v_readlane_b32 s36, v241, 33
	v_lshlrev_b32_e32 v147, 2, v146
	v_readlane_b32 s40, v241, 37
	v_readlane_b32 s41, v241, 38
	v_ashrrev_i32_e32 v138, 6, v137
	v_lshrrev_b32_e32 v96, 8, v137
	v_bfe_u32 v139, v137, 4, 2
	v_lshlrev_b32_e32 v145, 2, v139
	v_readlane_b32 s42, v241, 39
	s_waitcnt vmcnt(8)
	v_mov_b32_e32 v52, v156
	v_mov_b32_e32 v53, v157
	v_mov_b32_e32 v54, v158
	v_mov_b32_e32 v55, v159
	v_fmac_f32_e32 v42, v88, v52
	v_fmac_f32_e32 v72, v81, v53
	v_mul_f32_e32 v42, 0x4038aa3b, v42
	s_waitcnt vmcnt(8)
	v_mov_b32_e32 v48, v160
	v_mov_b32_e32 v49, v161
	v_mov_b32_e32 v50, v162
	v_mov_b32_e32 v51, v163
	v_fmac_f32_e32 v79, v80, v51
	v_exp_f32_e32 v42, v42
	v_mul_f32_e32 v51, 0x4038aa3b, v72
	v_exp_f32_e32 v53, v51
	v_fmac_f32_e32 v77, v78, v50
	v_lshlrev_b32_e32 v50, 16, v39
	v_add_f32_e32 v42, 1.0, v42
	v_fmac_f32_e32 v73, v82, v54
	v_cndmask_b32_e32 v51, 0, v87, vcc
	v_rcp_f32_e32 v52, v42
	v_add_f32_e32 v42, 1.0, v53
	v_cndmask_b32_e32 v50, 0, v50, vcc
	v_fmac_f32_e32 v74, v83, v55
	v_rcp_f32_e32 v53, v42
	v_pk_add_f32 v[50:51], v[50:51], v[64:65] neg_lo:[0,1] neg_hi:[0,1]
	v_mul_f32_e32 v42, 0x4038aa3b, v73
	s_waitcnt vmcnt(8)
	v_mov_b32_e32 v56, v168
	v_mov_b32_e32 v57, v169
	v_mov_b32_e32 v58, v170
	v_mov_b32_e32 v59, v171
	v_mov_b32_e32 v44, v176
	v_mov_b32_e32 v45, v177
	v_mov_b32_e32 v46, v178
	v_mov_b32_e32 v47, v179
	v_pk_fma_f32 v[54:55], v[50:51], v[46:47], v[64:65]
	v_exp_f32_e32 v42, v42
	v_mul_f32_e32 v50, 0x4038aa3b, v74
	v_exp_f32_e32 v51, v50
	v_pk_fma_f32 v[46:47], v[52:53], 2.0, 1.0 op_sel_hi:[1,0,0] neg_lo:[1,0,0] neg_hi:[1,0,0]
	v_add_f32_e32 v42, 1.0, v42
	v_fmac_f32_e32 v75, v84, v48
	v_cvt_pk_bf16_f32 v50, v46, v47
	v_rcp_f32_e32 v46, v42
	v_add_f32_e32 v42, 1.0, v51
	v_fmac_f32_e32 v76, v85, v49
	v_rcp_f32_e32 v47, v42
	v_mul_f32_e32 v42, 0x4038aa3b, v75
	v_exp_f32_e32 v42, v42
	v_mul_f32_e32 v51, 0x4038aa3b, v76
	v_exp_f32_e32 v51, v51
	v_mul_f32_e32 v53, 0x4038aa3b, v79
	v_add_f32_e32 v42, 1.0, v42
	v_rcp_f32_e32 v52, v42
	v_add_f32_e32 v42, 1.0, v51
	v_mul_f32_e32 v51, 0x4038aa3b, v77
	v_exp_f32_e32 v51, v51
	v_pk_fma_f32 v[40:41], v[66:67], v[56:57], v[40:41]
	v_exp_f32_e32 v57, v53
	v_rcp_f32_e32 v53, v42
	v_add_f32_e32 v42, 1.0, v51
	v_rcp_f32_e32 v56, v42
	v_add_f32_e32 v42, 1.0, v57
	v_rcp_f32_e32 v57, v42
	v_pk_fma_f32 v[46:47], v[46:47], 2.0, 1.0 op_sel_hi:[1,0,0] neg_lo:[1,0,0] neg_hi:[1,0,0]
	v_pk_fma_f32 v[48:49], v[68:69], v[58:59], v[60:61]
	v_cvt_pk_bf16_f32 v51, v46, v47
	v_pk_fma_f32 v[46:47], v[52:53], 2.0, 1.0 op_sel_hi:[1,0,0] neg_lo:[1,0,0] neg_hi:[1,0,0]
	v_pk_fma_f32 v[44:45], v[70:71], v[44:45], v[62:63]
	v_cvt_pk_bf16_f32 v52, v46, v47
	v_pk_fma_f32 v[46:47], v[56:57], 2.0, 1.0 op_sel_hi:[1,0,0] neg_lo:[1,0,0] neg_hi:[1,0,0]
	v_and_b32_e32 v42, 48, v137
	v_cvt_pk_bf16_f32 v53, v46, v47
	v_cvt_pk_bf16_f32 v46, v40, v41
	v_mul_lo_u32 v40, v141, s96
	v_lshlrev_b32_e32 v41, 1, v142
	v_cvt_pk_bf16_f32 v47, v48, v49
	v_cvt_pk_bf16_f32 v48, v44, v45
	v_cvt_pk_bf16_f32 v49, v54, v55
	v_add3_u32 v143, 0, v40, v41
	v_add3_u32 v40, s97, v40, v41
	ds_write_b128 v40, v[46:49]
	v_cndmask_b32_e64 v41, v123, v124, s[0:1]
	v_cndmask_b32_e64 v40, v125, v126, s[0:1]
	v_lshl_add_u64 v[40:41], v[40:41], 0, s[12:13]
	ds_write_b128 v143, v[50:53] offset:64512
	v_lshl_add_u64 v[40:41], v[40:41], 0, v[42:43]
	v_lshlrev_b32_e32 v44, 7, v135
	v_mov_b32_e32 v45, v43
	v_lshl_add_u64 v[40:41], v[40:41], 0, v[44:45]
	global_load_dwordx4 v[44:47], v147, s[30:31] offset:16
	global_load_dwordx4 v[52:55], v147, s[30:31]
	global_load_dwordx4 v[48:51], v147, s[40:41] offset:16
	global_load_dwordx4 v[64:67], v147, s[40:41]
	global_load_dwordx4 v[72:75], v147, s[40:41] offset:2064
	global_load_dwordx4 v[68:71], v147, s[40:41] offset:2048
	s_waitcnt lgkmcnt(0)
	s_barrier
	s_cmp_lg_u32 s101, 0
	s_cbranch_scc1 .Lres_skip_197
	global_load_dwordx4 v[180:183], v[40:41], off
	global_load_dwordx4 v[184:187], v[40:41], off offset:64
	global_load_dwordx4 v[188:191], v[40:41], off offset:2048
	global_load_dwordx4 v[192:195], v[40:41], off offset:2112
	s_mov_b32 s98, 0x1000
	s_mov_b32 s99, 0
	v_lshl_add_u64 v[242:243], v[40:41], 0, s[98:99]
	global_load_dwordx4 v[196:199], v[242:243], off
	global_load_dwordx4 v[200:203], v[242:243], off offset:64
	global_load_dwordx4 v[204:207], v[242:243], off offset:2048
	global_load_dwordx4 v[208:211], v[242:243], off offset:2112
.Lres_skip_197:
	v_cndmask_b32_e64 v60, v121, v122, s[0:1]
	s_movk_i32 s0, 0x1000
	v_add_co_u32_e64 v40, s[0:1], s0, v40
	v_lshlrev_b32_e32 v56, 4, v138
	s_nop 0
	v_addc_co_u32_e64 v41, s[0:1], 0, v41, s[0:1]
	v_and_b32_e32 v108, 48, v56
	v_or_b32_e32 v40, v108, v135
	v_mul_u32_u24_e32 v40, 0x90, v40
	v_add3_u32 v109, v60, v40, v42
	ds_read_b128 v[60:63], v109
	s_movk_i32 s1, 0x4100
	v_mad_i32_i24 v40, v96, s1, v127
	ds_read_b128 v[96:99], v109 offset:64
	v_or_b32_e32 v41, v108, v145
	v_lshlrev_b32_e32 v108, 2, v135
	v_mul_u32_u24_e32 v41, 0x104, v41
	v_add3_u32 v108, v40, v108, v41
	v_and_b32_e32 v41, 0xffff0000, v16
	v_lshlrev_b32_e32 v40, 16, v16
	v_readlane_b32 s43, v241, 40
	v_readlane_b32 s46, v241, 43
	v_readlane_b32 s47, v241, 44
	v_readlane_b32 s50, v241, 47
	v_readlane_b32 s51, v241, 48
	v_readlane_b32 s72, v241, 49
	v_readlane_b32 s73, v241, 50
	s_movk_i32 s1, 0x104
	v_mul_lo_u32 v148, v141, s1
	v_readlane_b32 s1, v241, 8
	s_waitcnt vmcnt(0) lgkmcnt(1)
	v_mov_b32_e32 v76, v180
	v_mov_b32_e32 v77, v181
	v_mov_b32_e32 v78, v182
	v_mov_b32_e32 v79, v183
	s_nop 1
	v_mfma_f32_16x16x32_bf16 v[60:63], v[60:63], v[76:79], 0
	v_and_b32_e32 v77, 0xffff0000, v20
	v_add3_u32 v76, s1, v148, v144
	s_lshl_b32 s0, s2, 3
	s_waitcnt vmcnt(0) lgkmcnt(0)
	v_mov_b32_e32 v80, v184
	v_mov_b32_e32 v81, v185
	v_mov_b32_e32 v82, v186
	v_mov_b32_e32 v83, v187
	s_nop 1
	v_mfma_f32_16x16x32_bf16 v[60:63], v[96:99], v[80:83], v[60:63]
	s_nop 7
	ds_write_b32 v108, v60
	ds_write_b32 v108, v61 offset:260
	ds_write_b32 v108, v62 offset:520
	ds_write_b32 v108, v63 offset:780
	ds_read_b128 v[60:63], v109
	ds_read_b128 v[78:81], v109 offset:64
	s_waitcnt vmcnt(0) lgkmcnt(1)
	v_mov_b32_e32 v84, v188
	v_mov_b32_e32 v85, v189
	v_mov_b32_e32 v86, v190
	v_mov_b32_e32 v87, v191
	s_nop 1
	v_mfma_f32_16x16x32_bf16 v[60:63], v[60:63], v[84:87], 0
	v_lshlrev_b32_e32 v84, 16, v20
	v_cndmask_b32_e32 v85, 0, v77, vcc
	v_cndmask_b32_e32 v84, 0, v84, vcc
	s_waitcnt vmcnt(0) lgkmcnt(0)
	v_mov_b32_e32 v88, v192
	v_mov_b32_e32 v89, v193
	v_mov_b32_e32 v90, v194
	v_mov_b32_e32 v91, v195
	s_nop 1
	v_mfma_f32_16x16x32_bf16 v[60:63], v[78:81], v[88:91], v[60:63]
	s_nop 7
	ds_write_b32 v108, v60 offset:64
	ds_write_b32 v108, v61 offset:324
	ds_write_b32 v108, v62 offset:584
	ds_write_b32 v108, v63 offset:844
	ds_read_b128 v[60:63], v109
	v_pk_add_f32 v[78:79], v[84:85], v[40:41] neg_lo:[0,1] neg_hi:[0,1]
	v_and_b32_e32 v77, 0xffff0000, v22
	v_pk_fma_f32 v[40:41], v[78:79], v[52:53], v[40:41]
	ds_read_b128 v[78:81], v109 offset:64
	s_waitcnt vmcnt(0) lgkmcnt(1)
	v_mov_b32_e32 v92, v196
	v_mov_b32_e32 v93, v197
	v_mov_b32_e32 v94, v198
	v_mov_b32_e32 v95, v199
	s_nop 1
	v_mfma_f32_16x16x32_bf16 v[60:63], v[60:63], v[92:95], 0
	v_lshlrev_b32_e32 v84, 16, v22
	v_and_b32_e32 v53, 0xffff0000, v18
	v_lshlrev_b32_e32 v52, 16, v18
	s_waitcnt vmcnt(0) lgkmcnt(0)
	v_mov_b32_e32 v100, v200
	v_mov_b32_e32 v101, v201
	v_mov_b32_e32 v102, v202
	v_mov_b32_e32 v103, v203
	s_nop 1
	v_mfma_f32_16x16x32_bf16 v[60:63], v[78:81], v[100:103], v[60:63]
	s_nop 7
	ds_write_b32 v108, v60 offset:128
	ds_write_b32 v108, v61 offset:388
	ds_write_b32 v108, v62 offset:648
	ds_write_b32 v108, v63 offset:908
	ds_read_b128 v[60:63], v109
	ds_read_b128 v[78:81], v109 offset:64
	v_cndmask_b32_e32 v85, 0, v77, vcc
	v_cndmask_b32_e32 v84, 0, v84, vcc
	v_pk_add_f32 v[84:85], v[84:85], v[52:53] neg_lo:[0,1] neg_hi:[0,1]
	s_waitcnt vmcnt(0) lgkmcnt(1)
	v_mov_b32_e32 v104, v204
	v_mov_b32_e32 v105, v205
	v_mov_b32_e32 v106, v206
	v_mov_b32_e32 v107, v207
	s_nop 1
	v_mfma_f32_16x16x32_bf16 v[60:63], v[60:63], v[104:107], 0
	v_fma_f32 v44, v84, v44, v52
	v_fma_f32 v45, v85, v45, v53
	v_and_b32_e32 v77, 0xffff0000, v21
	v_lshlrev_b32_e32 v84, 16, v21
	v_and_b32_e32 v53, 0xffff0000, v17
	v_lshlrev_b32_e32 v52, 16, v17
	v_cndmask_b32_e32 v85, 0, v77, vcc
	v_cndmask_b32_e32 v84, 0, v84, vcc
	v_pk_add_f32 v[84:85], v[84:85], v[52:53] neg_lo:[0,1] neg_hi:[0,1]
	v_and_b32_e32 v95, 0xffff0000, v19
	v_pk_fma_f32 v[84:85], v[84:85], v[54:55], v[52:53]
	s_waitcnt vmcnt(0) lgkmcnt(0)
	v_mov_b32_e32 v56, v208
	v_mov_b32_e32 v57, v209
	v_mov_b32_e32 v58, v210
	v_mov_b32_e32 v59, v211
	s_nop 1
	v_mfma_f32_16x16x32_bf16 v[52:55], v[78:81], v[56:59], v[60:63]
	s_nop 7
	ds_write_b32 v108, v52 offset:192
	ds_write_b32 v108, v53 offset:452
	ds_write_b32 v108, v54 offset:712
	ds_write_b32 v108, v55 offset:972
	s_waitcnt lgkmcnt(0)
	s_barrier
	s_cmp_lg_u32 s101, 0
	s_cbranch_scc1 .Lres_skip_355
	v_readlane_b32 s98, v241, 51
	v_readlane_b32 s99, v241, 52
	global_load_dwordx4 v[212:215], v147, s[42:43]
	global_load_dwordx4 v[216:219], v147, s[46:47]
	global_load_dwordx4 v[220:223], v147, s[42:43] offset:16
	global_load_dwordx4 v[224:227], v147, s[50:51]
	global_load_dwordx4 v[228:231], v147, s[72:73]
	global_load_dwordx4 v[232:235], v147, s[46:47] offset:16
	global_load_dwordx4 v[236:239], v147, s[50:51] offset:16
	global_load_dwordx4 v[244:247], v147, s[72:73] offset:16
	global_load_dwordx4 v[248:251], v147, s[98:99]
	global_load_dwordx4 v[252:255], v147, s[98:99] offset:16
.Lres_skip_355:
	v_and_b32_e32 v56, 0xffff0000, v23
	v_lshlrev_b32_e32 v58, 16, v23
	v_lshlrev_b32_e32 v94, 16, v19
	v_cndmask_b32_e32 v57, 0, v56, vcc
	v_cndmask_b32_e32 v56, 0, v58, vcc
	v_pk_add_f32 v[96:97], v[56:57], v[94:95] neg_lo:[0,1] neg_hi:[0,1]
	v_and_b32_e32 v56, 0xffff0000, v7
	v_lshlrev_b32_e32 v58, 16, v7
	v_and_b32_e32 v61, 0xffff0000, v3
	v_lshlrev_b32_e32 v60, 16, v3
	v_cndmask_b32_e32 v57, 0, v56, vcc
	v_cndmask_b32_e32 v56, 0, v58, vcc
	v_pk_add_f32 v[62:63], v[56:57], v[60:61] neg_lo:[0,1] neg_hi:[0,1]
	v_pk_fma_f32 v[88:89], v[62:63], v[50:51], v[60:61]
	v_and_b32_e32 v60, 0xffff0000, v15
	v_lshlrev_b32_e32 v62, 16, v15
	v_and_b32_e32 v51, 0xffff0000, v11
	v_lshlrev_b32_e32 v50, 16, v11
	v_cndmask_b32_e32 v61, 0, v60, vcc
	v_cndmask_b32_e32 v60, 0, v62, vcc
	v_pk_add_f32 v[60:61], v[60:61], v[50:51] neg_lo:[0,1] neg_hi:[0,1]
	v_lshlrev_b32_e32 v62, 16, v6
	v_pk_fma_f32 v[100:101], v[60:61], v[74:75], v[50:51]
	v_and_b32_e32 v60, 0xffff0000, v6
	v_and_b32_e32 v51, 0xffff0000, v2
	v_lshlrev_b32_e32 v50, 16, v2
	v_cndmask_b32_e32 v61, 0, v60, vcc
	v_cndmask_b32_e32 v60, 0, v62, vcc
	v_pk_add_f32 v[60:61], v[60:61], v[50:51] neg_lo:[0,1] neg_hi:[0,1]
	v_and_b32_e32 v75, 0xffff0000, v10
	v_pk_fma_f32 v[86:87], v[60:61], v[48:49], v[50:51]
	v_and_b32_e32 v48, 0xffff0000, v14
	v_lshlrev_b32_e32 v50, 16, v14
	v_lshlrev_b32_e32 v74, 16, v10
	v_cndmask_b32_e32 v49, 0, v48, vcc
	v_cndmask_b32_e32 v48, 0, v50, vcc
	v_pk_add_f32 v[78:79], v[48:49], v[74:75] neg_lo:[0,1] neg_hi:[0,1]
	v_pk_fma_f32 v[102:103], v[78:79], v[72:73], v[74:75]
	v_and_b32_e32 v74, 0xffff0000, v5
	v_lshlrev_b32_e32 v77, 16, v5
	v_and_b32_e32 v73, 0xffff0000, v1
	v_lshlrev_b32_e32 v72, 16, v1
	v_cndmask_b32_e32 v75, 0, v74, vcc
	v_cndmask_b32_e32 v74, 0, v77, vcc
	v_pk_add_f32 v[74:75], v[74:75], v[72:73] neg_lo:[0,1] neg_hi:[0,1]
	ds_read2_b32 v[80:81], v76 offset1:1
	v_pk_fma_f32 v[92:93], v[66:67], v[74:75], v[72:73]
	v_and_b32_e32 v72, 0xffff0000, v13
	v_lshlrev_b32_e32 v74, 16, v13
	v_and_b32_e32 v67, 0xffff0000, v9
	v_lshlrev_b32_e32 v66, 16, v9
	v_cndmask_b32_e32 v73, 0, v72, vcc
	v_cndmask_b32_e32 v72, 0, v74, vcc
	v_pk_add_f32 v[72:73], v[72:73], v[66:67] neg_lo:[0,1] neg_hi:[0,1]
	v_lshlrev_b32_e32 v74, 16, v12
	v_pk_fma_f32 v[104:105], v[72:73], v[70:71], v[66:67]
	v_and_b32_e32 v70, 0xffff0000, v4
	v_lshlrev_b32_e32 v72, 16, v4
	v_and_b32_e32 v67, 0xffff0000, v0
	v_lshlrev_b32_e32 v66, 16, v0
	v_cndmask_b32_e32 v71, 0, v70, vcc
	v_cndmask_b32_e32 v70, 0, v72, vcc
	v_pk_add_f32 v[70:71], v[70:71], v[66:67] neg_lo:[0,1] neg_hi:[0,1]
	v_and_b32_e32 v72, 0xffff0000, v12
	v_pk_fma_f32 v[90:91], v[64:65], v[70:71], v[66:67]
	v_and_b32_e32 v71, 0xffff0000, v8
	v_lshlrev_b32_e32 v70, 16, v8
	v_cndmask_b32_e32 v73, 0, v72, vcc
	v_cndmask_b32_e32 v72, 0, v74, vcc
	v_pk_add_f32 v[72:73], v[72:73], v[70:71] neg_lo:[0,1] neg_hi:[0,1]
	v_add_u32_e32 v99, 0x4100, v76
	v_pk_fma_f32 v[106:107], v[72:73], v[68:69], v[70:71]
	v_add_u32_e32 v83, 0x4108, v76
	v_add_u32_e32 v98, 0x4110, v76
	v_add_u32_e32 v82, 0x4118, v76
	ds_read2_b32 v[108:109], v76 offset0:2 offset1:3
	ds_read2_b32 v[110:111], v76 offset0:4 offset1:5
	ds_read2_b32 v[112:113], v76 offset0:6 offset1:7
	s_waitcnt vmcnt(0) lgkmcnt(3)
	v_mov_b32_e32 v52, v212
	v_mov_b32_e32 v53, v213
	v_mov_b32_e32 v54, v214
	v_mov_b32_e32 v55, v215
	v_add_f32_e32 v52, v52, v80
	v_mul_f32_e64 v68, |v52|, s91
	v_exp_f32_e32 v80, v68
	ds_read2_b32 v[150:151], v99 offset1:1
	ds_read2_b32 v[118:119], v83 offset1:1
	ds_read2_b32 v[116:117], v98 offset1:1
	ds_read2_b32 v[114:115], v82 offset1:1
	v_add_f32_e32 v80, 1.0, v80
	v_cmp_gt_f32_e32 vcc, s3, v80
	s_and_b32 s0, s0, 0xfffff000
	s_or_b32 s4, s4, s0
	v_cndmask_b32_e64 v99, 0, 32, vcc
	v_ldexp_f32 v80, v80, v99
	v_log_f32_e32 v80, v80
	v_max_f32_e64 v52, -v52, 0
	s_waitcnt vmcnt(0) lgkmcnt(3)
	v_mov_b32_e32 v56, v216
	v_mov_b32_e32 v57, v217
	v_mov_b32_e32 v58, v218
	v_mov_b32_e32 v59, v219
	v_add_f32_e32 v56, v56, v150
	v_mul_f32_e32 v56, 0xbfb8aa3b, v56
	v_mul_f32_e32 v82, 0x3f317217, v80
	v_fma_f32 v82, v80, s10, -v82
	v_fmac_f32_e32 v82, 0x3377d1cf, v80
	v_fmac_f32_e32 v82, 0x3f317217, v80
	v_cmp_lt_f32_e64 s[0:1], |v80|, s11
	v_add_f32_e32 v53, v53, v81
	v_exp_f32_e32 v56, v56
	v_cndmask_b32_e64 v80, v80, v82, s[0:1]
	v_cndmask_b32_e32 v82, 0, v128, vcc
	v_sub_f32_e32 v80, v80, v82
	v_add_f32_e32 v52, v52, v80
	v_mul_f32_e64 v80, |v53|, s91
	v_exp_f32_e32 v80, v80
	v_sub_f32_e32 v52, -0.5, v52
	v_mul_f32_e32 v52, 0x3fb8aa3b, v52
	v_exp_f32_e32 v98, v52
	v_add_f32_e32 v52, 1.0, v56
	v_rcp_f32_e32 v56, v52
	v_add_f32_e32 v52, 1.0, v80
	v_cmp_gt_f32_e32 vcc, s3, v52
	v_add_f32_e32 v57, v57, v151
	v_max_f32_e64 v53, -v53, 0
	v_cndmask_b32_e64 v80, 0, 32, vcc
	v_ldexp_f32 v52, v52, v80
	v_log_f32_e32 v52, v52
	s_waitcnt vmcnt(0)
	v_mov_b32_e32 v48, v220
	v_mov_b32_e32 v49, v221
	v_mov_b32_e32 v50, v222
	v_mov_b32_e32 v51, v223
	v_mov_b32_e32 v60, v224
	v_mov_b32_e32 v61, v225
	v_mov_b32_e32 v62, v226
	v_mov_b32_e32 v63, v227
	v_mul_f32_e32 v149, v106, v60
	v_add_f32_e32 v54, v54, v108
	v_mul_f32_e32 v150, v107, v61
	v_mul_f32_e32 v60, 0x3f317217, v52
	v_fma_f32 v60, v52, s10, -v60
	v_fmac_f32_e32 v60, 0x3377d1cf, v52
	v_fmac_f32_e32 v60, 0x3f317217, v52
	v_cmp_lt_f32_e64 s[0:1], |v52|, s11
	v_add_f32_e32 v48, v48, v110
	v_add_f32_e32 v49, v49, v111
	v_cndmask_b32_e64 v52, v52, v60, s[0:1]
	v_cndmask_b32_e32 v60, 0, v128, vcc
	v_sub_f32_e32 v52, v52, v60
	v_add_f32_e32 v52, v53, v52
	v_mul_f32_e32 v53, 0xbfb8aa3b, v57
	v_exp_f32_e32 v53, v53
	v_sub_f32_e32 v52, -0.5, v52
	v_mul_f32_e32 v52, 0x3fb8aa3b, v52
	v_exp_f32_e32 v99, v52
	v_add_f32_e32 v52, 1.0, v53
	v_rcp_f32_e32 v57, v52
	v_mul_f32_e64 v52, |v54|, s91
	v_exp_f32_e32 v60, v52
	v_readlane_b32 s74, v241, 51
	v_pk_add_f32 v[52:53], v[56:57], -1.0 op_sel_hi:[1,0]
	v_readlane_b32 s75, v241, 52
	v_add_f32_e32 v60, 1.0, v60
	v_cmp_gt_f32_e32 vcc, s3, v60
	s_waitcnt vmcnt(0)
	v_mov_b32_e32 v64, v228
	v_mov_b32_e32 v65, v229
	v_mov_b32_e32 v66, v230
	v_mov_b32_e32 v67, v231
	v_pk_fma_f32 v[52:53], v[64:65], v[52:53], 1.0 op_sel_hi:[1,1,0]
	v_add_f32_e32 v50, v50, v112
	v_cndmask_b32_e64 v61, 0, 32, vcc
	v_ldexp_f32 v60, v60, v61
	v_log_f32_e32 v64, v60
	v_pk_mul_f32 v[60:61], v[106:107], v[52:53]
	v_max_f32_e64 v53, -v54, 0
	s_waitcnt lgkmcnt(2)
	v_add_f32_e32 v52, v58, v118
	v_mul_f32_e32 v54, 0x3f317217, v64
	v_fma_f32 v54, v64, s10, -v54
	v_fmac_f32_e32 v54, 0x3377d1cf, v64
	v_fmac_f32_e32 v54, 0x3f317217, v64
	v_cmp_lt_f32_e64 s[0:1], |v64|, s11
	v_cndmask_b32_e32 v58, 0, v128, vcc
	v_mul_f32_e32 v52, 0xbfb8aa3b, v52
	v_cndmask_b32_e64 v54, v64, v54, s[0:1]
	v_sub_f32_e32 v54, v54, v58
	v_add_f32_e32 v53, v53, v54
	v_sub_f32_e32 v53, -0.5, v53
	v_mul_f32_e32 v53, 0x3fb8aa3b, v53
	v_exp_f32_e32 v58, v53
	v_add_f32_e32 v53, v55, v109
	v_exp_f32_e32 v52, v52
	v_mul_f32_e64 v54, |v53|, s91
	v_exp_f32_e32 v54, v54
	v_max_f32_e64 v53, -v53, 0
	v_add_f32_e32 v52, 1.0, v52
	v_rcp_f32_e32 v64, v52
	v_add_f32_e32 v52, 1.0, v54
	v_cmp_gt_f32_e32 vcc, s3, v52
	v_mul_f32_e32 v106, v104, v62
	v_mul_f32_e32 v107, v105, v63
	v_cndmask_b32_e64 v54, 0, 32, vcc
	v_ldexp_f32 v52, v52, v54
	v_log_f32_e32 v52, v52
	v_add_f32_e32 v54, v59, v119
	v_add_f32_e32 v51, v51, v113
	v_mul_f32_e32 v55, 0x3f317217, v52
	v_fma_f32 v55, v52, s10, -v55
	v_fmac_f32_e32 v55, 0x3377d1cf, v52
	v_fmac_f32_e32 v55, 0x3f317217, v52
	v_cmp_lt_f32_e64 s[0:1], |v52|, s11
	v_mul_f32_e32 v151, v150, v150
	v_fmac_f32_e32 v151, v149, v149
	v_cndmask_b32_e64 v52, v52, v55, s[0:1]
	v_cndmask_b32_e32 v55, 0, v128, vcc
	v_sub_f32_e32 v52, v52, v55
	v_add_f32_e32 v52, v53, v52
	v_mul_f32_e32 v53, 0xbfb8aa3b, v54
	v_exp_f32_e32 v53, v53
	v_sub_f32_e32 v52, -0.5, v52
	v_mul_f32_e32 v52, 0x3fb8aa3b, v52
	v_exp_f32_e32 v59, v52
	v_add_f32_e32 v52, 1.0, v53
	v_rcp_f32_e32 v65, v52
	v_mul_f32_e64 v52, |v48|, s91
	v_exp_f32_e32 v54, v52
	v_max_f32_e64 v48, -v48, 0
	v_pk_add_f32 v[52:53], v[64:65], -1.0 op_sel_hi:[1,0]
	v_fmac_f32_e32 v151, v106, v106
	v_add_f32_e32 v54, 1.0, v54
	v_cmp_gt_f32_e32 vcc, s3, v54
	v_pk_fma_f32 v[52:53], v[66:67], v[52:53], 1.0 op_sel_hi:[1,1,0]
	v_fmac_f32_e32 v151, v107, v107
	v_cndmask_b32_e64 v55, 0, 32, vcc
	v_ldexp_f32 v54, v54, v55
	v_log_f32_e32 v54, v54
	v_pk_mul_f32 v[62:63], v[104:105], v[52:53]
	s_waitcnt vmcnt(0) lgkmcnt(1)
	v_mov_b32_e32 v76, v232
	v_mov_b32_e32 v77, v233
	v_mov_b32_e32 v78, v234
	v_mov_b32_e32 v79, v235
	v_add_f32_e32 v52, v76, v116
	v_mul_f32_e32 v52, 0xbfb8aa3b, v52
	v_mul_f32_e32 v53, 0x3f317217, v54
	v_fma_f32 v53, v54, s10, -v53
	v_fmac_f32_e32 v53, 0x3377d1cf, v54
	v_fmac_f32_e32 v53, 0x3f317217, v54
	v_cmp_lt_f32_e64 s[0:1], |v54|, s11
	v_exp_f32_e32 v52, v52
	s_waitcnt vmcnt(0)
	v_mov_b32_e32 v72, v236
	v_mov_b32_e32 v73, v237
	v_mov_b32_e32 v74, v238
	v_mov_b32_e32 v75, v239
	v_mul_f32_e32 v76, v102, v72
	v_cndmask_b32_e64 v53, v54, v53, s[0:1]
	v_cndmask_b32_e32 v54, 0, v128, vcc
	v_sub_f32_e32 v53, v53, v54
	v_add_f32_e32 v48, v48, v53
	v_mul_f32_e64 v53, |v49|, s91
	v_exp_f32_e32 v53, v53
	v_add_f32_e32 v52, 1.0, v52
	v_rcp_f32_e32 v66, v52
	v_max_f32_e64 v49, -v49, 0
	v_add_f32_e32 v52, 1.0, v53
	v_cmp_gt_f32_e32 vcc, s3, v52
	v_mul_f32_e64 v72, |v50|, s91
	v_exp_f32_e32 v104, v72
	v_cndmask_b32_e64 v53, 0, 32, vcc
	v_ldexp_f32 v52, v52, v53
	v_log_f32_e32 v52, v52
	v_add_f32_e32 v53, v77, v117
	v_mul_f32_e32 v77, v103, v73
	v_max_f32_e64 v50, -v50, 0
	v_mul_f32_e32 v54, 0x3f317217, v52
	v_fma_f32 v54, v52, s10, -v54
	v_fmac_f32_e32 v54, 0x3377d1cf, v52
	v_fmac_f32_e32 v54, 0x3f317217, v52
	v_cmp_lt_f32_e64 s[0:1], |v52|, s11
	v_fmac_f32_e32 v151, v76, v76
	v_fmac_f32_e32 v151, v77, v77
	v_cndmask_b32_e64 v52, v52, v54, s[0:1]
	v_cndmask_b32_e32 v54, 0, v128, vcc
	v_sub_f32_e32 v52, v52, v54
	v_add_f32_e32 v49, v49, v52
	v_mul_f32_e32 v52, 0xbfb8aa3b, v53
	v_exp_f32_e32 v67, v52
	v_pk_fma_f32 v[46:47], v[96:97], v[46:47], v[94:95]
	v_sub_f32_e32 v48, -0.5, v48
	v_add_f32_e32 v67, 1.0, v67
	v_rcp_f32_e32 v67, v67
	v_sub_f32_e32 v49, -0.5, v49
	v_mul_f32_e32 v48, 0x3fb8aa3b, v48
	v_mul_f32_e32 v49, 0x3fb8aa3b, v49
	v_pk_add_f32 v[72:73], v[66:67], -1.0 op_sel_hi:[1,0]
	v_exp_f32_e32 v48, v48
	s_waitcnt vmcnt(0)
	v_mov_b32_e32 v68, v244
	v_mov_b32_e32 v69, v245
	v_mov_b32_e32 v70, v246
	v_mov_b32_e32 v71, v247
	v_pk_fma_f32 v[68:69], v[68:69], v[72:73], 1.0 op_sel_hi:[1,1,0]
	v_add_f32_e32 v72, 1.0, v104
	v_cmp_gt_f32_e32 vcc, s3, v72
	v_pk_mul_f32 v[68:69], v[102:103], v[68:69]
	v_exp_f32_e32 v49, v49
	v_cndmask_b32_e64 v73, 0, 32, vcc
	v_ldexp_f32 v72, v72, v73
	v_log_f32_e32 v72, v72
	s_waitcnt lgkmcnt(0)
	v_add_f32_e32 v73, v78, v114
	v_and_b32_e32 v140, 63, v137
	v_readlane_b32 s37, v241, 34
	v_mul_f32_e32 v78, 0x3f317217, v72
	v_fma_f32 v78, v72, s10, -v78
	v_fmac_f32_e32 v78, 0x3377d1cf, v72
	v_fmac_f32_e32 v78, 0x3f317217, v72
	v_cmp_lt_f32_e64 s[0:1], |v72|, s11
	v_readlane_b32 s38, v241, 35
	v_readlane_b32 s39, v241, 36
	v_cndmask_b32_e64 v72, v72, v78, s[0:1]
	v_cndmask_b32_e32 v78, 0, v128, vcc
	v_sub_f32_e32 v72, v72, v78
	v_add_f32_e32 v50, v50, v72
	v_mul_f32_e32 v72, 0xbfb8aa3b, v73
	v_mul_f32_e64 v73, |v51|, s91
	v_exp_f32_e32 v73, v73
	v_mul_f32_e32 v78, v100, v74
	v_exp_f32_e32 v72, v72
	v_max_f32_e64 v51, -v51, 0
	v_add_f32_e32 v73, 1.0, v73
	v_cmp_gt_f32_e32 vcc, s3, v73
	v_add_f32_e32 v72, 1.0, v72
	v_rcp_f32_e32 v72, v72
	v_cndmask_b32_e64 v74, 0, 32, vcc
	v_ldexp_f32 v73, v73, v74
	v_log_f32_e32 v73, v73
	v_add_f32_e32 v74, v79, v115
	v_mul_f32_e32 v74, 0xbfb8aa3b, v74
	v_exp_f32_e32 v74, v74
	v_mul_f32_e32 v79, 0x3f317217, v73
	v_fma_f32 v79, v73, s10, -v79
	v_fmac_f32_e32 v79, 0x3377d1cf, v73
	v_fmac_f32_e32 v79, 0x3f317217, v73
	v_cmp_lt_f32_e64 s[0:1], |v73|, s11
	v_fmac_f32_e32 v151, v78, v78
	v_sub_f32_e32 v50, -0.5, v50
	v_cndmask_b32_e64 v73, v73, v79, s[0:1]
	v_cndmask_b32_e32 v79, 0, v128, vcc
	v_sub_f32_e32 v73, v73, v79
	v_add_f32_e32 v51, v51, v73
	v_add_f32_e32 v73, 1.0, v74
	v_rcp_f32_e32 v73, v73
	v_mul_f32_e32 v79, v101, v75
	v_cmp_lt_i32_e32 vcc, v130, v131
	v_fmac_f32_e32 v151, v79, v79
	v_pk_add_f32 v[74:75], v[72:73], -1.0 op_sel_hi:[1,0]
	v_sub_f32_e32 v51, -0.5, v51
	v_pk_fma_f32 v[70:71], v[70:71], v[74:75], 1.0 op_sel_hi:[1,1,0]
	v_cndmask_b32_e32 v74, v129, v130, vcc
	v_pk_mul_f32 v[70:71], v[100:101], v[70:71]
	v_lshlrev_b32_e32 v100, 2, v74
	v_pk_mul_f32 v[74:75], v[90:91], v[60:61]
	v_cmp_lt_i32_e32 vcc, v132, v131
	s_waitcnt vmcnt(0)
	v_mov_b32_e32 v80, v248
	v_mov_b32_e32 v81, v249
	v_mov_b32_e32 v82, v250
	v_mov_b32_e32 v83, v251
	v_pk_mul_f32 v[74:75], v[74:75], v[80:81]
	v_mul_f32_e32 v50, 0x3fb8aa3b, v50
	v_add_f32_e32 v74, 0, v74
	v_add_f32_e32 v80, v74, v75
	v_pk_mul_f32 v[74:75], v[92:93], v[62:63]
	v_mul_f32_e32 v51, 0x3fb8aa3b, v51
	v_pk_mul_f32 v[74:75], v[74:75], v[82:83]
	v_mov_b32_e32 v81, v43
	v_add_f32_e32 v74, v80, v74
	v_add_f32_e32 v80, v74, v75
	v_pk_mul_f32 v[74:75], v[86:87], v[68:69]
	v_exp_f32_e32 v50, v50
	s_waitcnt vmcnt(0)
	v_mov_b32_e32 v52, v252
	v_mov_b32_e32 v53, v253
	v_mov_b32_e32 v54, v254
	v_mov_b32_e32 v55, v255
	v_pk_mul_f32 v[52:53], v[74:75], v[52:53]
	v_exp_f32_e32 v51, v51
	v_add_f32_e32 v52, v80, v52
	v_add_f32_e32 v74, v52, v53
	v_pk_mul_f32 v[52:53], v[88:89], v[70:71]
	v_lshlrev_b32_e32 v80, 1, v146
	v_pk_mul_f32 v[52:53], v[52:53], v[54:55]
	v_cndmask_b32_e32 v54, v129, v132, vcc
	v_add_f32_e32 v52, v74, v52
	v_add_f32_e32 v52, v52, v53
	ds_bpermute_b32 v53, v100, v52
	v_lshlrev_b32_e32 v54, 2, v54
	v_cmp_lt_i32_e32 vcc, v133, v131
	ds_bpermute_b32 v55, v100, v151
	s_movk_i32 s0, 0x820
	s_waitcnt lgkmcnt(1)
	v_add_f32_e32 v52, v52, v53
	ds_bpermute_b32 v53, v54, v52
	v_cndmask_b32_e32 v74, v129, v133, vcc
	v_lshlrev_b32_e32 v82, 2, v74
	s_waitcnt lgkmcnt(1)
	v_add_f32_e32 v83, v151, v55
	ds_bpermute_b32 v100, v54, v83
	s_waitcnt lgkmcnt(1)
	v_add_f32_e32 v52, v52, v53
	ds_bpermute_b32 v53, v82, v52
	v_cmp_lt_i32_e32 vcc, 0, v138
	v_readlane_b32 s44, v241, 41
	v_readlane_b32 s45, v241, 42
	v_readlane_b32 s48, v241, 45
	s_waitcnt lgkmcnt(0)
	v_add_f32_e32 v74, v52, v53
	v_pk_mul_f32 v[52:53], v[40:41], v[74:75] op_sel_hi:[1,0]
	v_pk_mul_f32 v[54:55], v[84:85], v[74:75] op_sel_hi:[1,0]
	v_cvt_pk_bf16_f32 v52, v52, v53
	v_cvt_pk_bf16_f32 v53, v54, v55
	v_pk_mul_f32 v[54:55], v[44:45], v[74:75] op_sel_hi:[1,0]
	v_pk_mul_f32 v[74:75], v[46:47], v[74:75] op_sel_hi:[1,0]
	v_cvt_pk_bf16_f32 v54, v54, v55
	v_cvt_pk_bf16_f32 v55, v74, v75
	v_add_u32_e32 v74, s4, v141
	v_ashrrev_i32_e32 v75, 31, v74
	v_lshlrev_b64 v[74:75], 10, v[74:75]
	v_lshl_add_u64 v[74:75], s[52:53], 0, v[74:75]
	v_lshl_add_u64 v[74:75], v[74:75], 0, v[80:81]
	global_store_dwordx4 v[74:75], v[52:55], off nt
	s_waitcnt lgkmcnt(0)
	s_barrier
	v_readlane_b32 s49, v241, 46
	v_add3_u32 v54, s94, v148, v144
	v_pk_add_f32 v[52:53], v[98:99], 0 neg_lo:[1,1] neg_hi:[1,1]
	ds_write2_b32 v54, v52, v53 offset1:1
	v_pk_add_f32 v[52:53], v[58:59], 0 neg_lo:[1,1] neg_hi:[1,1]
	ds_write2_b32 v54, v52, v53 offset0:2 offset1:3
	v_pk_add_f32 v[52:53], v[48:49], 0 neg_lo:[1,1] neg_hi:[1,1]
	ds_write2_b32 v54, v52, v53 offset0:4 offset1:5
	v_pk_add_f32 v[52:53], v[50:51], 0 neg_lo:[1,1] neg_hi:[1,1]
	ds_write2_b32 v54, v52, v53 offset0:6 offset1:7
	v_lshl_add_u32 v52, v140, 2, s94
	v_mul_lo_u32 v53, v138, s0
	s_waitcnt lgkmcnt(0)
	s_barrier
	v_add_u32_e32 v53, v52, v53
	ds_read2_b32 v[74:75], v53 offset1:65
	v_add_f32_e32 v55, v83, v100
	ds_bpermute_b32 v80, v82, v55
	ds_read2_b32 v[82:83], v53 offset0:130 offset1:195
	v_readlane_b32 s76, v241, 53
	s_waitcnt lgkmcnt(2)
	v_add_f32_e32 v52, 0, v74
	v_add_f32_e32 v81, v52, v75
	ds_write2_b32 v53, v52, v81 offset1:65
	v_add_u32_e32 v52, 0x400, v53
	ds_read2_b32 v[74:75], v52 offset0:4 offset1:69
	s_waitcnt lgkmcnt(2)
	v_add_f32_e32 v81, v81, v82
	v_add_f32_e32 v94, v81, v83
	ds_read2_b32 v[82:83], v52 offset0:134 offset1:199
	ds_write2_b32 v53, v81, v94 offset0:130 offset1:195
	s_waitcnt lgkmcnt(2)
	v_add_f32_e32 v74, v94, v74
	v_add_f32_e32 v75, v74, v75
	ds_write2_b32 v52, v74, v75 offset0:4 offset1:69
	s_waitcnt lgkmcnt(2)
	v_add_f32_e32 v74, v75, v82
	v_add_f32_e32 v75, v74, v83
	ds_write2_b32 v52, v74, v75 offset0:134 offset1:199
	v_lshl_add_u32 v74, v137, 2, 0
	v_add_u32_e32 v74, 0x24000, v74
	ds_write_b32 v74, v75
	s_waitcnt lgkmcnt(0)
	s_barrier
	v_mov_b32_e32 v81, 0
	v_readlane_b32 s77, v241, 54
	v_readlane_b32 s78, v241, 55
	v_readlane_b32 s79, v241, 56
	v_readlane_b32 s80, v241, 57
	v_readlane_b32 s81, v241, 58
	v_readlane_b32 s82, v241, 59
	v_readlane_b32 s83, v241, 60
	v_readlane_b32 s84, v241, 61
	v_readlane_b32 s85, v241, 62
	v_readlane_b32 s86, v241, 63
	v_readlane_b32 s87, v240, 0
	s_and_saveexec_b64 s[0:1], vcc
	s_cbranch_execz .LBB0_783
	v_cmp_lt_u32_e32 vcc, 7, v138
	v_mov_b32_e32 v81, 0
	v_mov_b32_e32 v74, 0
	s_and_saveexec_b64 s[4:5], vcc
	s_cbranch_execz .LBB0_778
	s_add_i32 s6, 0, 0x24000
	v_and_b32_e32 v74, 0x7ffffff8, v138
	v_lshl_add_u32 v75, v140, 2, s6
	s_mov_b32 s12, 0
	v_mov_b32_e32 v81, 0
	s_mov_b64 s[6:7], 0

.LBB0_814:
	s_or_b64 exec, exec, s[0:1]
	s_movk_i32 s0, 0x900
	v_mul_lo_u32 v40, v138, s0
	v_lshrrev_b32_e32 v69, 2, v140
	v_lshlrev_b32_e32 v41, 5, v137
	v_add_u32_e32 v68, s94, v40
	v_mul_u32_u24_e32 v40, 0x90, v69
	v_and_b32_e32 v41, 0x60, v41
	v_add3_u32 v40, v68, v40, v41
	s_add_i32 s2, s2, s88
	ds_write_b128 v40, v[152:155]
	ds_write_b128 v40, v[152:155] offset:16
	s_waitcnt lgkmcnt(0)
	s_barrier
	s_cmpk_gt_i32 s2, 0xfff
	s_cselect_b64 s[4:5], -1, 0
	s_and_b64 vcc, exec, s[4:5]
	s_cbranch_vccnz .LBB0_826
	v_mov_b32_e32 v0, v174
	s_lshl_b32 s0, s2, 6
	v_ashrrev_i32_e32 v4, 3, v0
	v_lshlrev_b32_e32 v0, 3, v0
	v_and_b32_e32 v28, 56, v0
	s_and_b32 s0, s0, 0x1c0
	s_lshl_b32 s6, s2, 3
	v_readlane_b32 s36, v240, 1
	v_or_b32_e32 v2, s0, v28
	s_and_b32 s0, s6, 0xffffffc0
	v_readlane_b32 s40, v240, 5
	v_readlane_b32 s41, v240, 6
	v_add_u32_e32 v3, s0, v4
	s_movk_i32 s0, 0x1040
	v_mov_b64_e32 v[0:1], s[40:41]
	v_mad_i64_i32 v[24:25], s[0:1], v3, s0, v[0:1]
	v_lshlrev_b32_e32 v42, 1, v2
	v_lshl_add_u64 v[26:27], v[24:25], 0, v[42:43]
	global_load_dwordx4 v[0:3], v[26:27], off offset:832
	s_and_b32 s0, s6, 0xfc0
	v_add_u32_e32 v4, s0, v4
	v_cmp_lt_i32_e32 vcc, 0, v4
	v_readlane_b32 s37, v240, 2
	v_readlane_b32 s38, v240, 3
	v_readlane_b32 s39, v240, 4
	v_readlane_b32 s42, v240, 7
	v_readlane_b32 s43, v240, 8
	v_readlane_b32 s44, v240, 9
	v_readlane_b32 s45, v240, 10
	v_readlane_b32 s46, v240, 11
	v_readlane_b32 s47, v240, 12
	v_readlane_b32 s48, v240, 13
	v_readlane_b32 s49, v240, 14
	v_readlane_b32 s50, v240, 15
	v_readlane_b32 s51, v240, 16
	global_load_dwordx4 v[8:11], v[26:27], off offset:1856
	global_load_dwordx4 v[16:19], v[26:27], off offset:2880
	v_lshlrev_b32_e32 v42, 1, v28
	v_lshl_add_u64 v[40:41], v[24:25], 0, v[42:43]
	s_and_saveexec_b64 s[0:1], vcc
	global_load_dwordx4 v[4:7], v[26:27], off offset:-3328
	global_load_dwordx4 v[12:15], v[26:27], off offset:-2304
	global_load_dwordx4 v[20:23], v[26:27], off offset:-1280
	global_load_dwordx4 v[28:31], v[40:41], off offset:-256
	global_load_dwordx4 v[36:39], v[40:41], off offset:-128
	s_or_b64 exec, exec, s[0:1]
	global_load_dwordx4 v[24:27], v[40:41], off offset:3904
	global_load_dwordx4 v[32:35], v[40:41], off offset:4032
